# fused attention pipes: empty s_setprio 1/0 pairs (dead issue slots) deleted at 6 sites
# speedup vs baseline: 1.0038x; 1.0038x over previous
; #define LAS __attribute__((address_space(3)))
; DI float ex2(float x) { return __builtin_amdgcn_exp2f(x); }
; template <int MM> DI void smax_step_nb(const f32x16& s, unsigned vm, float& m, float& l, f32x16 (&o)[2], bf16x8 (&pf)[2], int lane) {
;     float mx = -1e30f;
; #pragma unroll
;     for (int i = 0; i < 16; ++i) mx = fmaxf(mx, s[i]);
;     if (MM == 1) mx = vm ? mx : -1e30f;
;     mx = fmaxf(mx, shx32(mx, lane));
;     const float mn = (mx > m + 8.0f) ? mx : m;
;     float mref = fmaxf(mn, -1e29f);
;     if (MM == 1) mref = vm ? mref : 3e38f;
;     const float alpha = ex2(m - mn);
;     float p[16], rs = 0.f;
; #pragma unroll
;     for (int i = 0; i < 16; ++i) { p[i] = ex2(s[i] - mref); rs += p[i]; }
;     rs += shx32(rs, lane);
;     l = l * alpha + rs;
;     if (__builtin_amdgcn_ballot_w64(mn != m) != 0ull) {
; #pragma unroll
;         for (int i = 0; i < 16; ++i) { o[0][i] *= alpha; o[1][i] *= alpha; }
;     }
;     m = mn;
;     pack_p(p, pf);
; }
; template <int MODE, bool PRE = false> ...
;     ...
;             const int kt0 = kt_lo + 2 * sti;
;             bool both = (kt0 + 1 <= kt_hi) && (64 * kt0 + 127 <= q0w);
;             if (MODE == MODE_NWIN) both = both && (64 * kt0 > q0w + 31 - 512);
;             if (both) {
;                 bool ls0 = true, ls1 = true;
;                 if (MODE == MODE_MOBA) { ls0 = ((sel >> (kt0 >> 2)) & 1ull) != 0ull; ls1 = ((sel >> ((kt0 + 1) >> 2)) & 1ull) != 0ull; }
;                 if (MODE == MODE_NSEL) { ls0 = ((sel >> kt0) & 1ull) != 0ull; ls1 = ((sel >> (kt0 + 1)) & 1ull) != 0ull; }
;                 const unsigned long long b0 = __builtin_amdgcn_ballot_w64(ls0), b1 = __builtin_amdgcn_ballot_w64(ls1);
;                 if (b0 != 0ull && b1 != 0ull) {
;                     LAS char* K0 = lds + (sti & 1) * 4 * TILE_B;
;                     if ((b0 & b1) == ~0ull) tile128_pipe<0>(K0, K0 + TILE_B, K0 + 2 * TILE_B, K0 + 3 * TILE_B, qf, 1u, 1u, m1, l1, o1, r, h, lane);
;                     else tile128_pipe<1>(K0, K0 + TILE_B, K0 + 2 * TILE_B, K0 + 3 * TILE_B, qf, ls0 ? 1u : 0u, ls1 ? 1u : 0u, m1, l1, o1, r, h, lane);
.LBB0_589:
	s_lshl_b32 s64, s48, 1
	s_cmp_lt_u32 s64, s58
	s_cselect_b64 s[0:1], -1, 0
	s_lshl_b32 s10, s48, 7
	s_or_b32 s10, s10, 0x7f
	s_cmp_le_i32 s10, s59
	s_cselect_b64 s[10:11], -1, 0
	s_and_b64 s[0:1], s[0:1], s[10:11]
	s_andn2_b64 vcc, exec, s[0:1]
	s_mov_b32 s10, 0
	s_cbranch_vccnz .LBB0_612
	s_or_b32 s0, s64, 1
	v_lshrrev_b64 v[32:33], s64, v[164:165]
	v_and_b32_e32 v34, 1, v32
	v_lshrrev_b64 v[32:33], s0, v[164:165]
	v_and_b32_e32 v32, 1, v32
	v_cmp_ne_u32_e64 s[40:41], 0, v34
	v_cmp_ne_u32_e64 s[42:43], 0, v32
	s_cmp_eq_u64 s[40:41], 0
	s_cselect_b64 s[34:35], -1, 0
	s_cmp_eq_u64 s[42:43], 0
	s_cselect_b64 s[56:57], -1, 0
	s_or_b64 s[34:35], s[34:35], s[56:57]
	v_cmp_eq_u32_e64 s[38:39], 1, v34
	v_cmp_eq_u32_e64 s[0:1], 1, v32
	s_and_b64 vcc, exec, s[34:35]
	s_cbranch_vccnz .LBB0_612
	s_lshl_b32 s10, s48, 2
	s_and_b32 s10, s10, 4
	s_mulk_i32 s10, 0x2400
	s_add_i32 s10, s10, 0
	v_add_u32_e32 v32, s10, v190
	v_add_u32_e32 v215, v32, v168
	s_waitcnt lgkmcnt(7)
	ds_read_b128 v[140:143], v215
	s_waitcnt lgkmcnt(7)
	ds_read_b128 v[136:139], v215 offset:32
	s_waitcnt lgkmcnt(7)
	ds_read_b128 v[132:135], v215 offset:64
	s_waitcnt lgkmcnt(7)
	ds_read_b128 v[128:131], v215 offset:96
	s_and_b64 s[34:35], s[42:43], s[40:41]
	s_cmp_lg_u64 s[34:35], -1
	s_waitcnt lgkmcnt(7)
	ds_read_b128 v[144:147], v215 offset:4608
	s_waitcnt lgkmcnt(7)
	ds_read_b128 v[148:151], v215 offset:4640
	s_waitcnt lgkmcnt(7)
	ds_read_b128 v[152:155], v215 offset:4672
	s_waitcnt lgkmcnt(7)
	ds_read_b128 v[156:159], v215 offset:4704
	v_add_f32_e32 v216, 0x41000000, v214
	s_cbranch_scc0 .LBB0_601
	s_waitcnt lgkmcnt(7)
	v_mfma_f32_32x32x16_bf16 v[32:47], v[140:143], v[96:99], 0
	s_waitcnt lgkmcnt(6)
	v_mfma_f32_32x32x16_bf16 v[32:47], v[136:139], v[100:103], v[32:47]
	s_waitcnt lgkmcnt(5)
	v_mfma_f32_32x32x16_bf16 v[32:47], v[132:135], v[104:107], v[32:47]
	s_waitcnt lgkmcnt(4)
	v_mfma_f32_32x32x16_bf16 v[32:47], v[128:131], v[108:111], v[32:47]
	s_waitcnt lgkmcnt(3)
	v_mfma_f32_32x32x16_bf16 v[64:79], v[144:147], v[96:99], 0
	s_nop 9
	v_max3_f32 v48, v32, s15, v33
	v_max3_f32 v48, v48, v34, v35
	v_max3_f32 v48, v48, v36, v37
	v_max3_f32 v48, v48, v38, v39
	v_max3_f32 v48, v48, v40, v41
	v_max3_f32 v48, v48, v42, v43
	v_max3_f32 v48, v48, v44, v45
	v_max3_f32 v48, v48, v46, v47
	v_cndmask_b32_e64 v48, v208, v48, s[38:39]
	v_mov_b32_e32 v49, v48
	v_mov_b32_e32 v50, v48
	s_nop 1
	v_permlane32_swap_b32_e32 v49, v50
	v_max_f32_e32 v48, v49, v50
	v_cmp_gt_f32_e32 vcc, v48, v216
	s_waitcnt lgkmcnt(2)
	v_mfma_f32_32x32x16_bf16 v[64:79], v[148:151], v[100:103], v[64:79]
	v_cndmask_b32_e32 v224, v214, v48, vcc
	v_max_f32_e32 v48, 0xefa18f08, v224
	v_cndmask_b32_e64 v48, v209, v48, s[38:39]
	v_sub_f32_e32 v32, v32, v48
	v_sub_f32_e32 v33, v33, v48
	v_exp_f32_e32 v80, v32
	v_sub_f32_e32 v34, v34, v48
	v_exp_f32_e32 v81, v33
	v_sub_f32_e32 v35, v35, v48
	v_exp_f32_e32 v82, v34
	v_sub_f32_e32 v36, v36, v48
	v_exp_f32_e32 v83, v35
	v_sub_f32_e32 v37, v37, v48
	v_exp_f32_e32 v84, v36
	v_sub_f32_e32 v38, v38, v48
	v_exp_f32_e32 v85, v37
	v_add_f32_e32 v32, v81, v80
	v_sub_f32_e32 v39, v39, v48
	v_exp_f32_e32 v86, v38
	s_waitcnt lgkmcnt(1)
	v_mfma_f32_32x32x16_bf16 v[64:79], v[152:155], v[104:107], v[64:79]
	v_add_f32_e32 v32, v82, v32
	v_sub_f32_e32 v40, v40, v48
	v_exp_f32_e32 v87, v39
	v_add_f32_e32 v32, v83, v32
	v_sub_f32_e32 v41, v41, v48
	v_exp_f32_e32 v88, v40
	v_add_f32_e32 v32, v84, v32
	v_sub_f32_e32 v42, v42, v48
	v_exp_f32_e32 v89, v41
	v_add_f32_e32 v32, v85, v32
	v_sub_f32_e32 v43, v43, v48
	v_exp_f32_e32 v90, v42
	v_add_f32_e32 v32, v86, v32
	v_sub_f32_e32 v44, v44, v48
	v_exp_f32_e32 v91, v43
	v_add_f32_e32 v32, v87, v32
	v_add_f32_e32 v32, v88, v32
	v_exp_f32_e32 v92, v44
	v_sub_f32_e32 v33, v45, v48
	v_add_f32_e32 v32, v89, v32
	v_exp_f32_e32 v93, v33
	v_sub_f32_e32 v33, v46, v48
	s_waitcnt lgkmcnt(0)
	v_mfma_f32_32x32x16_bf16 v[64:79], v[156:159], v[108:111], v[64:79]
	v_add_f32_e32 v32, v90, v32
	v_exp_f32_e32 v94, v33
	v_sub_f32_e32 v33, v47, v48
	v_add_f32_e32 v32, v91, v32
	v_exp_f32_e32 v95, v33
	v_add_f32_e32 v32, v92, v32
	v_sub_f32_e32 v49, v214, v224
	v_add_f32_e32 v32, v93, v32
	v_add_f32_e32 v32, v94, v32
	v_exp_f32_e32 v166, v49
	v_add_f32_e32 v217, v95, v32
	v_mov_b32_e32 v218, v217
	v_mov_b32_e32 v219, v217
	s_nop 0
	s_nop 0
	v_permlane32_swap_b32_e32 v218, v219
	v_cmp_neq_f32_e32 vcc, v224, v214
	s_cbranch_vccz .LBB0_594
	v_pk_mul_f32 v[30:31], v[30:31], v[166:167] op_sel_hi:[1,0]
	v_pk_mul_f32 v[28:29], v[28:29], v[166:167] op_sel_hi:[1,0]
	v_pk_mul_f32 v[26:27], v[26:27], v[166:167] op_sel_hi:[1,0]
	v_pk_mul_f32 v[24:25], v[24:25], v[166:167] op_sel_hi:[1,0]
	v_pk_mul_f32 v[22:23], v[22:23], v[166:167] op_sel_hi:[1,0]
	v_pk_mul_f32 v[20:21], v[20:21], v[166:167] op_sel_hi:[1,0]
	v_pk_mul_f32 v[18:19], v[18:19], v[166:167] op_sel_hi:[1,0]
	v_pk_mul_f32 v[16:17], v[16:17], v[166:167] op_sel_hi:[1,0]
	v_pk_mul_f32 v[14:15], v[14:15], v[166:167] op_sel_hi:[1,0]
	v_pk_mul_f32 v[12:13], v[12:13], v[166:167] op_sel_hi:[1,0]
	v_pk_mul_f32 v[10:11], v[10:11], v[166:167] op_sel_hi:[1,0]
	v_pk_mul_f32 v[8:9], v[8:9], v[166:167] op_sel_hi:[1,0]
	v_pk_mul_f32 v[6:7], v[6:7], v[166:167] op_sel_hi:[1,0]
	v_pk_mul_f32 v[4:5], v[4:5], v[166:167] op_sel_hi:[1,0]
	v_pk_mul_f32 v[2:3], v[2:3], v[166:167] op_sel_hi:[1,0]
	v_pk_mul_f32 v[0:1], v[0:1], v[166:167] op_sel_hi:[1,0]

; #define LAS __attribute__((address_space(3)))
; DI float ex2(float x) { return __builtin_amdgcn_exp2f(x); }
; template <int MM> DI void smax_step_nb(const f32x16& s, unsigned vm, float& m, float& l, f32x16 (&o)[2], bf16x8 (&pf)[2], int lane) {
;     float mx = -1e30f;
; #pragma unroll
;     for (int i = 0; i < 16; ++i) mx = fmaxf(mx, s[i]);
;     if (MM == 1) mx = vm ? mx : -1e30f;
;     mx = fmaxf(mx, shx32(mx, lane));
;     const float mn = (mx > m + 8.0f) ? mx : m;
;     float mref = fmaxf(mn, -1e29f);
;     if (MM == 1) mref = vm ? mref : 3e38f;
;     const float alpha = ex2(m - mn);
;     float p[16], rs = 0.f;
; #pragma unroll
;     for (int i = 0; i < 16; ++i) { p[i] = ex2(s[i] - mref); rs += p[i]; }
;     rs += shx32(rs, lane);
;     l = l * alpha + rs;
;     if (__builtin_amdgcn_ballot_w64(mn != m) != 0ull) {
; #pragma unroll
;         for (int i = 0; i < 16; ++i) { o[0][i] *= alpha; o[1][i] *= alpha; }
;     }
;     m = mn;
;     pack_p(p, pf);
; }
; template <int MODE, bool PRE = false> ...
;     ...
;             const int kt0 = kt_lo + 2 * sti;
;             bool both = (kt0 + 1 <= kt_hi) && (64 * kt0 + 127 <= q0w);
;             if (MODE == MODE_NWIN) both = both && (64 * kt0 > q0w + 31 - 512);
;             if (both) {
;                 bool ls0 = true, ls1 = true;
;                 if (MODE == MODE_MOBA) { ls0 = ((sel >> (kt0 >> 2)) & 1ull) != 0ull; ls1 = ((sel >> ((kt0 + 1) >> 2)) & 1ull) != 0ull; }
;                 if (MODE == MODE_NSEL) { ls0 = ((sel >> kt0) & 1ull) != 0ull; ls1 = ((sel >> (kt0 + 1)) & 1ull) != 0ull; }
;                 const unsigned long long b0 = __builtin_amdgcn_ballot_w64(ls0), b1 = __builtin_amdgcn_ballot_w64(ls1);
;                 if (b0 != 0ull && b1 != 0ull) {
;                     LAS char* K0 = lds + (sti & 1) * 4 * TILE_B;
;                     if ((b0 & b1) == ~0ull) tile128_pipe<0>(K0, K0 + TILE_B, K0 + 2 * TILE_B, K0 + 3 * TILE_B, qf, 1u, 1u, m1, l1, o1, r, h, lane);
;                     else tile128_pipe<1>(K0, K0 + TILE_B, K0 + 2 * TILE_B, K0 + 3 * TILE_B, qf, ls0 ? 1u : 0u, ls1 ? 1u : 0u, m1, l1, o1, r, h, lane);
.LBB0_675:
	s_lshl_b32 s62, s44, 1
	s_add_i32 s62, s62, s27
	s_cmp_lt_u32 s62, s58
	s_cselect_b64 s[0:1], -1, 0
	s_lshl_b32 s24, s62, 6
	s_add_i32 s10, s24, 0x7f
	s_cmp_le_i32 s10, s59
	s_cselect_b64 s[10:11], -1, 0
	s_and_b64 s[0:1], s[0:1], s[10:11]
	s_cmp_gt_i32 s24, s57
	s_cselect_b64 s[10:11], -1, 0
	s_and_b64 s[0:1], s[0:1], s[10:11]
	s_andn2_b64 vcc, exec, s[0:1]
	s_mov_b32 s0, 0
	s_cbranch_vccnz .LBB0_698
	s_cmp_eq_u64 exec, 0
	s_cbranch_scc1 .LBB0_698
	s_lshl_b32 s0, s44, 2
	s_and_b32 s0, s0, 4
	s_mulk_i32 s0, 0x2400
	s_add_i32 s10, s0, 0
	v_add_u32_e32 v32, s10, v190
	v_add_u32_e32 v212, v32, v168
	s_waitcnt lgkmcnt(7)
	ds_read_b128 v[140:143], v212
	s_waitcnt lgkmcnt(7)
	ds_read_b128 v[136:139], v212 offset:32
	s_waitcnt lgkmcnt(7)
	ds_read_b128 v[132:135], v212 offset:64
	s_waitcnt lgkmcnt(7)
	ds_read_b128 v[128:131], v212 offset:96
	s_cmp_lg_u64 exec, -1
	s_waitcnt lgkmcnt(7)
	ds_read_b128 v[144:147], v212 offset:4608
	s_waitcnt lgkmcnt(7)
	ds_read_b128 v[148:151], v212 offset:4640
	s_waitcnt lgkmcnt(7)
	ds_read_b128 v[152:155], v212 offset:4672
	s_waitcnt lgkmcnt(7)
	ds_read_b128 v[156:159], v212 offset:4704
	v_add_f32_e32 v213, 0x41000000, v193
	s_cbranch_scc0 .LBB0_687
	s_waitcnt lgkmcnt(7)
	v_mfma_f32_32x32x16_bf16 v[32:47], v[140:143], v[96:99], 0
	s_waitcnt lgkmcnt(6)
	v_mfma_f32_32x32x16_bf16 v[32:47], v[136:139], v[100:103], v[32:47]
	s_waitcnt lgkmcnt(5)
	v_mfma_f32_32x32x16_bf16 v[32:47], v[132:135], v[104:107], v[32:47]
	s_waitcnt lgkmcnt(4)
	v_mfma_f32_32x32x16_bf16 v[32:47], v[128:131], v[108:111], v[32:47]
	s_waitcnt lgkmcnt(3)
	v_mfma_f32_32x32x16_bf16 v[64:79], v[144:147], v[96:99], 0
	s_nop 9
	v_max3_f32 v48, v32, s15, v33
	v_max3_f32 v48, v48, v34, v35
	v_max3_f32 v48, v48, v36, v37
	v_max3_f32 v48, v48, v38, v39
	v_max3_f32 v48, v48, v40, v41
	v_max3_f32 v48, v48, v42, v43
	v_max3_f32 v48, v48, v44, v45
	v_max3_f32 v48, v48, v46, v47
	v_mov_b32_e32 v49, v48
	v_mov_b32_e32 v50, v48
	s_nop 1
	v_permlane32_swap_b32_e32 v49, v50
	v_max_f32_e32 v48, v49, v50
	v_cmp_gt_f32_e32 vcc, v48, v213
	s_waitcnt lgkmcnt(2)
	v_mfma_f32_32x32x16_bf16 v[64:79], v[148:151], v[100:103], v[64:79]
	v_cndmask_b32_e32 v221, v193, v48, vcc
	v_max_f32_e32 v48, 0xefa18f08, v221
	v_sub_f32_e32 v32, v32, v48
	v_sub_f32_e32 v33, v33, v48
	v_exp_f32_e32 v80, v32
	v_sub_f32_e32 v34, v34, v48
	v_exp_f32_e32 v81, v33
	v_sub_f32_e32 v35, v35, v48
	v_exp_f32_e32 v82, v34
	v_sub_f32_e32 v36, v36, v48
	v_exp_f32_e32 v83, v35
	v_sub_f32_e32 v37, v37, v48
	v_exp_f32_e32 v84, v36
	v_sub_f32_e32 v38, v38, v48
	v_exp_f32_e32 v85, v37
	v_add_f32_e32 v32, v81, v80
	v_sub_f32_e32 v39, v39, v48
	v_exp_f32_e32 v86, v38
	s_waitcnt lgkmcnt(1)
	v_mfma_f32_32x32x16_bf16 v[64:79], v[152:155], v[104:107], v[64:79]
	v_add_f32_e32 v32, v82, v32
	v_sub_f32_e32 v40, v40, v48
	v_exp_f32_e32 v87, v39
	v_add_f32_e32 v32, v83, v32
	v_sub_f32_e32 v41, v41, v48
	v_exp_f32_e32 v88, v40
	v_add_f32_e32 v32, v84, v32
	v_sub_f32_e32 v42, v42, v48
	v_exp_f32_e32 v89, v41
	v_add_f32_e32 v32, v85, v32
	v_sub_f32_e32 v43, v43, v48
	v_exp_f32_e32 v90, v42
	v_add_f32_e32 v32, v86, v32
	v_sub_f32_e32 v44, v44, v48
	v_exp_f32_e32 v91, v43
	v_add_f32_e32 v32, v87, v32
	v_add_f32_e32 v32, v88, v32
	v_exp_f32_e32 v92, v44
	v_sub_f32_e32 v33, v45, v48
	v_add_f32_e32 v32, v89, v32
	v_exp_f32_e32 v93, v33
	v_sub_f32_e32 v33, v46, v48
	s_waitcnt lgkmcnt(0)
	v_mfma_f32_32x32x16_bf16 v[64:79], v[156:159], v[108:111], v[64:79]
	v_add_f32_e32 v32, v90, v32
	v_exp_f32_e32 v94, v33
	v_sub_f32_e32 v33, v47, v48
	v_add_f32_e32 v32, v91, v32
	v_exp_f32_e32 v95, v33
	v_add_f32_e32 v32, v92, v32
	v_sub_f32_e32 v49, v193, v221
	v_add_f32_e32 v32, v93, v32
	v_add_f32_e32 v32, v94, v32
	v_exp_f32_e32 v164, v49
	v_add_f32_e32 v214, v95, v32
	v_mov_b32_e32 v215, v214
	v_mov_b32_e32 v216, v214
	s_nop 0
	s_nop 0
	v_permlane32_swap_b32_e32 v215, v216
	v_cmp_neq_f32_e32 vcc, v221, v193
	s_cbranch_vccz .LBB0_680
	v_pk_mul_f32 v[30:31], v[30:31], v[164:165] op_sel_hi:[1,0]
	v_pk_mul_f32 v[28:29], v[28:29], v[164:165] op_sel_hi:[1,0]
	v_pk_mul_f32 v[26:27], v[26:27], v[164:165] op_sel_hi:[1,0]
	v_pk_mul_f32 v[24:25], v[24:25], v[164:165] op_sel_hi:[1,0]
	v_pk_mul_f32 v[22:23], v[22:23], v[164:165] op_sel_hi:[1,0]
	v_pk_mul_f32 v[20:21], v[20:21], v[164:165] op_sel_hi:[1,0]
	v_pk_mul_f32 v[18:19], v[18:19], v[164:165] op_sel_hi:[1,0]
	v_pk_mul_f32 v[16:17], v[16:17], v[164:165] op_sel_hi:[1,0]
	v_pk_mul_f32 v[14:15], v[14:15], v[164:165] op_sel_hi:[1,0]
	v_pk_mul_f32 v[12:13], v[12:13], v[164:165] op_sel_hi:[1,0]
	v_pk_mul_f32 v[10:11], v[10:11], v[164:165] op_sel_hi:[1,0]
	v_pk_mul_f32 v[8:9], v[8:9], v[164:165] op_sel_hi:[1,0]
	v_pk_mul_f32 v[6:7], v[6:7], v[164:165] op_sel_hi:[1,0]
	v_pk_mul_f32 v[4:5], v[4:5], v[164:165] op_sel_hi:[1,0]
	v_pk_mul_f32 v[2:3], v[2:3], v[164:165] op_sel_hi:[1,0]
	v_pk_mul_f32 v[0:1], v[0:1], v[164:165] op_sel_hi:[1,0]

; #define LAS __attribute__((address_space(3)))
; DI float ex2(float x) { return __builtin_amdgcn_exp2f(x); }
; template <int MM> DI void smax_step_nb(const f32x16& s, unsigned vm, float& m, float& l, f32x16 (&o)[2], bf16x8 (&pf)[2], int lane) {
;     float mx = -1e30f;
; #pragma unroll
;     for (int i = 0; i < 16; ++i) mx = fmaxf(mx, s[i]);
;     if (MM == 1) mx = vm ? mx : -1e30f;
;     mx = fmaxf(mx, shx32(mx, lane));
;     const float mn = (mx > m + 8.0f) ? mx : m;
;     float mref = fmaxf(mn, -1e29f);
;     if (MM == 1) mref = vm ? mref : 3e38f;
;     const float alpha = ex2(m - mn);
;     float p[16], rs = 0.f;
; #pragma unroll
;     for (int i = 0; i < 16; ++i) { p[i] = ex2(s[i] - mref); rs += p[i]; }
;     rs += shx32(rs, lane);
;     l = l * alpha + rs;
;     if (__builtin_amdgcn_ballot_w64(mn != m) != 0ull) {
; #pragma unroll
;         for (int i = 0; i < 16; ++i) { o[0][i] *= alpha; o[1][i] *= alpha; }
;     }
;     m = mn;
;     pack_p(p, pf);
; }
; template <int MODE, bool PRE = false> ...
;     ...
;             const int kt0 = kt_lo + 2 * sti;
;             bool both = (kt0 + 1 <= kt_hi) && (64 * kt0 + 127 <= q0w);
;             if (MODE == MODE_NWIN) both = both && (64 * kt0 > q0w + 31 - 512);
;             if (both) {
;                 bool ls0 = true, ls1 = true;
;                 if (MODE == MODE_MOBA) { ls0 = ((sel >> (kt0 >> 2)) & 1ull) != 0ull; ls1 = ((sel >> ((kt0 + 1) >> 2)) & 1ull) != 0ull; }
;                 if (MODE == MODE_NSEL) { ls0 = ((sel >> kt0) & 1ull) != 0ull; ls1 = ((sel >> (kt0 + 1)) & 1ull) != 0ull; }
;                 const unsigned long long b0 = __builtin_amdgcn_ballot_w64(ls0), b1 = __builtin_amdgcn_ballot_w64(ls1);
;                 if (b0 != 0ull && b1 != 0ull) {
;                     LAS char* K0 = lds + (sti & 1) * 4 * TILE_B;
;                     if ((b0 & b1) == ~0ull) tile128_pipe<0>(K0, K0 + TILE_B, K0 + 2 * TILE_B, K0 + 3 * TILE_B, qf, 1u, 1u, m1, l1, o1, r, h, lane);
;                     else tile128_pipe<1>(K0, K0 + TILE_B, K0 + 2 * TILE_B, K0 + 3 * TILE_B, qf, ls0 ? 1u : 0u, ls1 ? 1u : 0u, m1, l1, o1, r, h, lane);
.LBB0_849:
	s_lshl_b32 s62, s38, 1
	s_cmp_lt_u32 s62, s58
	s_cselect_b64 s[0:1], -1, 0
	s_lshl_b32 s10, s38, 7
	s_or_b32 s10, s10, 0x7f
	s_cmp_le_i32 s10, s27
	s_cselect_b64 s[10:11], -1, 0
	s_and_b64 s[0:1], s[0:1], s[10:11]
	s_andn2_b64 vcc, exec, s[0:1]
	s_mov_b32 s10, 0
	s_cbranch_vccnz .LBB0_872
	s_lshr_b32 s0, s38, 1
	v_lshrrev_b64 v[32:33], s0, v[168:169]
	v_and_b32_e32 v32, 1, v32
	v_cmp_eq_u32_e64 s[0:1], 1, v32
	v_cmp_ne_u32_e32 vcc, 0, v32
	s_cbranch_vccz .LBB0_872
	s_lshl_b32 s10, s38, 2
	s_and_b32 s10, s10, 4
	s_mulk_i32 s10, 0x2400
	s_add_i32 s10, s10, 0
	v_add_u32_e32 v32, s10, v184
	v_add_u32_e32 v192, v32, v160
	s_waitcnt lgkmcnt(7)
	ds_read_b128 v[140:143], v192
	s_waitcnt lgkmcnt(7)
	ds_read_b128 v[136:139], v192 offset:32
	s_waitcnt lgkmcnt(7)
	ds_read_b128 v[132:135], v192 offset:64
	s_waitcnt lgkmcnt(7)
	ds_read_b128 v[128:131], v192 offset:96
	s_cmp_lg_u64 vcc, -1
	s_waitcnt lgkmcnt(7)
	ds_read_b128 v[144:147], v192 offset:4608
	s_waitcnt lgkmcnt(7)
	ds_read_b128 v[148:151], v192 offset:4640
	s_waitcnt lgkmcnt(7)
	ds_read_b128 v[152:155], v192 offset:4672
	s_waitcnt lgkmcnt(7)
	ds_read_b128 v[156:159], v192 offset:4704
	v_add_f32_e32 v193, 0x41000000, v191
	s_cbranch_scc0 .LBB0_861
	s_waitcnt lgkmcnt(7)
	v_mfma_f32_32x32x16_bf16 v[32:47], v[140:143], v[112:115], 0
	s_waitcnt lgkmcnt(6)
	v_mfma_f32_32x32x16_bf16 v[32:47], v[136:139], v[116:119], v[32:47]
	s_waitcnt lgkmcnt(5)
	v_mfma_f32_32x32x16_bf16 v[32:47], v[132:135], v[120:123], v[32:47]
	s_waitcnt lgkmcnt(4)
	v_mfma_f32_32x32x16_bf16 v[32:47], v[128:131], v[124:127], v[32:47]
	s_waitcnt lgkmcnt(3)
	v_mfma_f32_32x32x16_bf16 v[64:79], v[144:147], v[112:115], 0
	s_nop 9
	v_max3_f32 v48, v32, s15, v33
	v_max3_f32 v48, v48, v34, v35
	v_max3_f32 v48, v48, v36, v37
	v_max3_f32 v48, v48, v38, v39
	v_max3_f32 v48, v48, v40, v41
	v_max3_f32 v48, v48, v42, v43
	v_max3_f32 v48, v48, v44, v45
	v_max3_f32 v48, v48, v46, v47
	v_cndmask_b32_e64 v48, v208, v48, s[0:1]
	v_mov_b32_e32 v49, v48
	v_mov_b32_e32 v50, v48
	s_nop 1
	v_permlane32_swap_b32_e32 v49, v50
	v_max_f32_e32 v48, v49, v50
	v_cmp_gt_f32_e32 vcc, v48, v193
	s_waitcnt lgkmcnt(2)
	v_mfma_f32_32x32x16_bf16 v[64:79], v[148:151], v[116:119], v[64:79]
	v_cndmask_b32_e32 v219, v191, v48, vcc
	v_max_f32_e32 v48, 0xefa18f08, v219
	v_cndmask_b32_e64 v48, v209, v48, s[0:1]
	v_sub_f32_e32 v32, v32, v48
	v_sub_f32_e32 v33, v33, v48
	v_exp_f32_e32 v80, v32
	v_sub_f32_e32 v34, v34, v48
	v_exp_f32_e32 v81, v33
	v_sub_f32_e32 v35, v35, v48
	v_exp_f32_e32 v82, v34
	v_sub_f32_e32 v36, v36, v48
	v_exp_f32_e32 v83, v35
	v_sub_f32_e32 v37, v37, v48
	v_exp_f32_e32 v84, v36
	v_sub_f32_e32 v38, v38, v48
	v_exp_f32_e32 v85, v37
	v_add_f32_e32 v32, v81, v80
	v_sub_f32_e32 v39, v39, v48
	v_exp_f32_e32 v86, v38
	s_waitcnt lgkmcnt(1)
	v_mfma_f32_32x32x16_bf16 v[64:79], v[152:155], v[120:123], v[64:79]
	v_add_f32_e32 v32, v82, v32
	v_sub_f32_e32 v40, v40, v48
	v_exp_f32_e32 v87, v39
	v_add_f32_e32 v32, v83, v32
	v_sub_f32_e32 v41, v41, v48
	v_exp_f32_e32 v88, v40
	v_add_f32_e32 v32, v84, v32
	v_sub_f32_e32 v42, v42, v48
	v_exp_f32_e32 v89, v41
	v_add_f32_e32 v32, v85, v32
	v_sub_f32_e32 v43, v43, v48
	v_exp_f32_e32 v90, v42
	v_add_f32_e32 v32, v86, v32
	v_sub_f32_e32 v44, v44, v48
	v_exp_f32_e32 v91, v43
	v_add_f32_e32 v32, v87, v32
	v_add_f32_e32 v32, v88, v32
	v_exp_f32_e32 v92, v44
	v_sub_f32_e32 v33, v45, v48
	v_add_f32_e32 v32, v89, v32
	v_exp_f32_e32 v93, v33
	v_sub_f32_e32 v33, v46, v48
	s_waitcnt lgkmcnt(0)
	v_mfma_f32_32x32x16_bf16 v[64:79], v[156:159], v[124:127], v[64:79]
	v_add_f32_e32 v32, v90, v32
	v_exp_f32_e32 v94, v33
	v_sub_f32_e32 v33, v47, v48
	v_add_f32_e32 v32, v91, v32
	v_exp_f32_e32 v95, v33
	v_add_f32_e32 v32, v92, v32
	v_sub_f32_e32 v49, v191, v219
	v_add_f32_e32 v32, v93, v32
	v_add_f32_e32 v32, v94, v32
	v_exp_f32_e32 v164, v49
	v_add_f32_e32 v212, v95, v32
	v_mov_b32_e32 v213, v212
	v_mov_b32_e32 v214, v212
	s_nop 0
	s_nop 0
	v_permlane32_swap_b32_e32 v213, v214
	v_cmp_neq_f32_e32 vcc, v219, v191
	s_cbranch_vccz .LBB0_854
	v_pk_mul_f32 v[30:31], v[30:31], v[164:165] op_sel_hi:[1,0]
	v_pk_mul_f32 v[28:29], v[28:29], v[164:165] op_sel_hi:[1,0]
	v_pk_mul_f32 v[26:27], v[26:27], v[164:165] op_sel_hi:[1,0]
	v_pk_mul_f32 v[24:25], v[24:25], v[164:165] op_sel_hi:[1,0]
	v_pk_mul_f32 v[22:23], v[22:23], v[164:165] op_sel_hi:[1,0]
	v_pk_mul_f32 v[20:21], v[20:21], v[164:165] op_sel_hi:[1,0]
	v_pk_mul_f32 v[18:19], v[18:19], v[164:165] op_sel_hi:[1,0]
	v_pk_mul_f32 v[16:17], v[16:17], v[164:165] op_sel_hi:[1,0]
	v_pk_mul_f32 v[14:15], v[14:15], v[164:165] op_sel_hi:[1,0]
	v_pk_mul_f32 v[12:13], v[12:13], v[164:165] op_sel_hi:[1,0]
	v_pk_mul_f32 v[10:11], v[10:11], v[164:165] op_sel_hi:[1,0]
	v_pk_mul_f32 v[8:9], v[8:9], v[164:165] op_sel_hi:[1,0]
	v_pk_mul_f32 v[6:7], v[6:7], v[164:165] op_sel_hi:[1,0]
	v_pk_mul_f32 v[4:5], v[4:5], v[164:165] op_sel_hi:[1,0]
	v_pk_mul_f32 v[2:3], v[2:3], v[164:165] op_sel_hi:[1,0]
	v_pk_mul_f32 v[0:1], v[0:1], v[164:165] op_sel_hi:[1,0]
